# RESID epilogue: 15 xor-16/xor-32 butterfly adds use v_permlane16/32_swap instead of ds_bpermute_b32
# speedup vs baseline: 1.0001x; 1.0001x over previous
.LBB0_649:
	s_add_i32 s42, s4, 2
	s_add_i32 s43, 0, 0x10000
	s_cmp_eq_u32 s35, s4
	v_lshl_add_u64 v[132:133], v[130:131], 0, s[84:85]
	s_cselect_b64 vcc, -1, 0
	v_add_u32_e32 v144, s43, v237
	v_cndmask_b32_e32 v157, v133, v177, vcc
	v_cndmask_b32_e32 v156, v132, v176, vcc
	ds_read_b128 v[132:135], v144
	ds_read_b128 v[136:139], v144 offset:1024
	ds_read_b128 v[140:143], v144 offset:2048
	ds_read_b128 v[144:147], v144 offset:3072
	s_cselect_b32 s4, s0, s6
	s_cselect_b32 s5, s1, s7
	v_lshl_add_u64 v[202:203], v[130:131], 0, v[172:173]
	s_add_i32 m0, s8, 0xc000
	ds_read_b128 v[148:151], v243
	ds_read_b128 v[152:155], v243 offset:1024
	ds_read_b128 v[178:181], v243 offset:2048
	ds_read_b128 v[182:185], v243 offset:3072
	ds_read_b128 v[186:189], v243 offset:4096
	ds_read_b128 v[190:193], v243 offset:5120
	ds_read_b128 v[194:197], v243 offset:6144
	ds_read_b128 v[198:201], v243 offset:7168
	global_load_lds_dwordx4 v[202:203], off
	v_lshl_add_u64 v[202:203], v[130:131], 0, v[174:175]
	s_add_i32 m0, s8, 0xe000
	s_nop 0
	global_load_lds_dwordx4 v[202:203], off
	s_waitcnt lgkmcnt(8)
	s_barrier
	s_waitcnt lgkmcnt(0)
	s_waitcnt lgkmcnt(0)
	v_mfma_f32_16x16x32_bf16 v[126:129], v[132:135], v[148:151], v[126:129]
	v_mfma_f32_16x16x32_bf16 v[122:125], v[140:143], v[148:151], v[122:125]
	v_mfma_f32_16x16x32_bf16 v[110:113], v[132:135], v[178:181], v[110:113]
	v_mfma_f32_16x16x32_bf16 v[106:109], v[140:143], v[178:181], v[106:109]
	v_mfma_f32_16x16x32_bf16 v[98:101], v[132:135], v[186:189], v[98:101]
	v_mfma_f32_16x16x32_bf16 v[90:93], v[140:143], v[186:189], v[90:93]
	v_mfma_f32_16x16x32_bf16 v[82:85], v[132:135], v[194:197], v[82:85]
	v_mfma_f32_16x16x32_bf16 v[74:77], v[140:143], v[194:197], v[74:77]
	v_mfma_f32_16x16x32_bf16 v[126:129], v[136:139], v[152:155], v[126:129]
	v_mfma_f32_16x16x32_bf16 v[122:125], v[144:147], v[152:155], v[122:125]
	v_mfma_f32_16x16x32_bf16 v[110:113], v[136:139], v[182:185], v[110:113]
	v_mfma_f32_16x16x32_bf16 v[106:109], v[144:147], v[182:185], v[106:109]
	v_mfma_f32_16x16x32_bf16 v[98:101], v[136:139], v[190:193], v[98:101]
	v_mfma_f32_16x16x32_bf16 v[90:93], v[144:147], v[190:193], v[90:93]
	v_mfma_f32_16x16x32_bf16 v[82:85], v[136:139], v[198:201], v[82:85]
	v_mfma_f32_16x16x32_bf16 v[74:77], v[144:147], v[198:201], v[74:77]
	s_barrier
	s_add_i32 s89, 0, 0x14000
	s_add_i32 s43, s43, s3
	v_add_u32_e32 v169, s89, v237
	v_lshl_add_u64 v[218:219], s[4:5], 0, v[162:163]
	s_mov_b32 m0, s43
	ds_read_b128 v[202:205], v169
	ds_read_b128 v[206:209], v169 offset:1024
	ds_read_b128 v[210:213], v169 offset:2048
	ds_read_b128 v[214:217], v169 offset:3072
	global_load_lds_dwordx4 v[218:219], off
	v_lshl_add_u64 v[224:225], s[4:5], 0, v[166:167]
	s_add_i32 m0, s43, 0x2000
	s_nop 0
	global_load_lds_dwordx4 v[224:225], off
	s_barrier
	s_waitcnt lgkmcnt(0)
	s_waitcnt lgkmcnt(0)
	v_mfma_f32_16x16x32_bf16 v[118:121], v[202:205], v[148:151], v[118:121]
	v_mfma_f32_16x16x32_bf16 v[114:117], v[210:213], v[148:151], v[114:117]
	v_mfma_f32_16x16x32_bf16 v[102:105], v[202:205], v[178:181], v[102:105]
	v_mfma_f32_16x16x32_bf16 v[94:97], v[210:213], v[178:181], v[94:97]
	v_mfma_f32_16x16x32_bf16 v[86:89], v[202:205], v[186:189], v[86:89]
	v_mfma_f32_16x16x32_bf16 v[78:81], v[210:213], v[186:189], v[78:81]
	v_mfma_f32_16x16x32_bf16 v[70:73], v[202:205], v[194:197], v[70:73]
	v_mfma_f32_16x16x32_bf16 v[66:69], v[210:213], v[194:197], v[66:69]
	v_mfma_f32_16x16x32_bf16 v[118:121], v[206:209], v[152:155], v[118:121]
	v_mfma_f32_16x16x32_bf16 v[114:117], v[214:217], v[152:155], v[114:117]
	v_mfma_f32_16x16x32_bf16 v[102:105], v[206:209], v[182:185], v[102:105]
	v_mfma_f32_16x16x32_bf16 v[94:97], v[214:217], v[182:185], v[94:97]
	v_mfma_f32_16x16x32_bf16 v[86:89], v[206:209], v[190:193], v[86:89]
	v_mfma_f32_16x16x32_bf16 v[78:81], v[214:217], v[190:193], v[78:81]
	v_mfma_f32_16x16x32_bf16 v[70:73], v[206:209], v[198:201], v[70:73]
	v_mfma_f32_16x16x32_bf16 v[66:69], v[214:217], v[198:201], v[66:69]
	s_mov_b32 m0, s8
	v_lshl_add_u64 v[230:231], v[156:157], 0, v[160:161]
	s_barrier
	ds_read_b128 v[148:151], v243 offset:16384
	ds_read_b128 v[152:155], v243 offset:17408
	ds_read_b128 v[178:181], v243 offset:18432
	ds_read_b128 v[182:185], v243 offset:19456
	ds_read_b128 v[186:189], v243 offset:20480
	ds_read_b128 v[190:193], v243 offset:21504
	ds_read_b128 v[194:197], v243 offset:22528
	ds_read_b128 v[198:201], v243 offset:23552
	global_load_lds_dwordx4 v[230:231], off
	v_lshl_add_u64 v[232:233], v[156:157], 0, v[164:165]
	s_mov_b32 m0, s9
	s_nop 0
	global_load_lds_dwordx4 v[232:233], off
	s_barrier
	s_waitcnt lgkmcnt(0)
	s_waitcnt lgkmcnt(0)
	v_mfma_f32_16x16x32_bf16 v[62:65], v[132:135], v[148:151], v[62:65]
	v_mfma_f32_16x16x32_bf16 v[58:61], v[140:143], v[148:151], v[58:61]
	v_mfma_f32_16x16x32_bf16 v[46:49], v[132:135], v[178:181], v[46:49]
	v_mfma_f32_16x16x32_bf16 v[42:45], v[140:143], v[178:181], v[42:45]
	v_mfma_f32_16x16x32_bf16 v[34:37], v[132:135], v[186:189], v[34:37]
	v_mfma_f32_16x16x32_bf16 v[26:29], v[140:143], v[186:189], v[26:29]
	v_mfma_f32_16x16x32_bf16 v[18:21], v[132:135], v[194:197], v[18:21]
	v_mfma_f32_16x16x32_bf16 v[10:13], v[140:143], v[194:197], v[10:13]
	v_mfma_f32_16x16x32_bf16 v[62:65], v[136:139], v[152:155], v[62:65]
	v_mfma_f32_16x16x32_bf16 v[58:61], v[144:147], v[152:155], v[58:61]
	v_mfma_f32_16x16x32_bf16 v[46:49], v[136:139], v[182:185], v[46:49]
	v_mfma_f32_16x16x32_bf16 v[42:45], v[144:147], v[182:185], v[42:45]
	v_mfma_f32_16x16x32_bf16 v[34:37], v[136:139], v[190:193], v[34:37]
	v_mfma_f32_16x16x32_bf16 v[26:29], v[144:147], v[190:193], v[26:29]
	v_mfma_f32_16x16x32_bf16 v[18:21], v[136:139], v[198:201], v[18:21]
	v_mfma_f32_16x16x32_bf16 v[10:13], v[144:147], v[198:201], v[10:13]
	s_barrier
	s_add_u32 s4, s4, s94
	s_addc_u32 s5, s5, 0
	s_add_i32 s43, s89, s3
	v_lshl_add_u64 v[244:245], s[4:5], 0, v[162:163]
	s_mov_b32 m0, s43
	v_lshl_add_u64 v[246:247], s[4:5], 0, v[166:167]
	global_load_lds_dwordx4 v[244:245], off
	s_add_i32 m0, s43, 0x2000
	s_nop 0
	global_load_lds_dwordx4 v[246:247], off
	s_waitcnt vmcnt(6)
	s_barrier
	v_mfma_f32_16x16x32_bf16 v[54:57], v[202:205], v[148:151], v[54:57]
	v_mfma_f32_16x16x32_bf16 v[50:53], v[210:213], v[148:151], v[50:53]
	v_mfma_f32_16x16x32_bf16 v[38:41], v[202:205], v[178:181], v[38:41]
	v_mfma_f32_16x16x32_bf16 v[30:33], v[210:213], v[178:181], v[30:33]
	v_mfma_f32_16x16x32_bf16 v[22:25], v[202:205], v[186:189], v[22:25]
	v_mfma_f32_16x16x32_bf16 v[14:17], v[210:213], v[186:189], v[14:17]
	v_mfma_f32_16x16x32_bf16 v[6:9], v[202:205], v[194:197], v[6:9]
	v_mfma_f32_16x16x32_bf16 v[2:5], v[210:213], v[194:197], v[2:5]
	v_mfma_f32_16x16x32_bf16 v[54:57], v[206:209], v[152:155], v[54:57]
	v_mfma_f32_16x16x32_bf16 v[50:53], v[214:217], v[152:155], v[50:53]
	v_mfma_f32_16x16x32_bf16 v[38:41], v[206:209], v[182:185], v[38:41]
	v_mfma_f32_16x16x32_bf16 v[30:33], v[214:217], v[182:185], v[30:33]
	v_mfma_f32_16x16x32_bf16 v[22:25], v[206:209], v[190:193], v[22:25]
	v_mfma_f32_16x16x32_bf16 v[14:17], v[214:217], v[190:193], v[14:17]
	v_mfma_f32_16x16x32_bf16 v[6:9], v[206:209], v[198:201], v[6:9]
	v_mfma_f32_16x16x32_bf16 v[2:5], v[214:217], v[198:201], v[2:5]
	s_add_i32 s4, 0, 0x18000
	v_add_u32_e32 v144, s4, v237
	s_barrier
	ds_read_b128 v[132:135], v144
	ds_read_b128 v[136:139], v144 offset:1024
	ds_read_b128 v[140:143], v144 offset:2048
	ds_read_b128 v[144:147], v144 offset:3072
	v_lshl_add_u64 v[156:157], v[156:157], 0, s[94:95]
	s_mov_b32 m0, s10
	v_lshl_add_u64 v[202:203], v[156:157], 0, v[160:161]
	ds_read_b128 v[148:151], v243 offset:32768
	ds_read_b128 v[152:155], v243 offset:33792
	ds_read_b128 v[178:181], v243 offset:34816
	ds_read_b128 v[182:185], v243 offset:35840
	ds_read_b128 v[186:189], v243 offset:36864
	ds_read_b128 v[190:193], v243 offset:37888
	ds_read_b128 v[194:197], v243 offset:38912
	ds_read_b128 v[198:201], v243 offset:39936
	global_load_lds_dwordx4 v[202:203], off
	v_lshl_add_u64 v[156:157], v[156:157], 0, v[164:165]
	s_mov_b32 m0, s11
	s_nop 0
	global_load_lds_dwordx4 v[156:157], off
	s_waitcnt lgkmcnt(8)
	s_barrier
	s_waitcnt lgkmcnt(0)
	s_waitcnt lgkmcnt(0)
	v_mfma_f32_16x16x32_bf16 v[126:129], v[132:135], v[148:151], v[126:129]
	v_mfma_f32_16x16x32_bf16 v[122:125], v[140:143], v[148:151], v[122:125]
	v_mfma_f32_16x16x32_bf16 v[110:113], v[132:135], v[178:181], v[110:113]
	v_mfma_f32_16x16x32_bf16 v[106:109], v[140:143], v[178:181], v[106:109]
	v_mfma_f32_16x16x32_bf16 v[98:101], v[132:135], v[186:189], v[98:101]
	v_mfma_f32_16x16x32_bf16 v[90:93], v[140:143], v[186:189], v[90:93]
	v_mfma_f32_16x16x32_bf16 v[82:85], v[132:135], v[194:197], v[82:85]
	v_mfma_f32_16x16x32_bf16 v[74:77], v[140:143], v[194:197], v[74:77]
	v_mfma_f32_16x16x32_bf16 v[126:129], v[136:139], v[152:155], v[126:129]
	v_mfma_f32_16x16x32_bf16 v[122:125], v[144:147], v[152:155], v[122:125]
	v_mfma_f32_16x16x32_bf16 v[110:113], v[136:139], v[182:185], v[110:113]
	v_mfma_f32_16x16x32_bf16 v[106:109], v[144:147], v[182:185], v[106:109]
	v_mfma_f32_16x16x32_bf16 v[98:101], v[136:139], v[190:193], v[98:101]
	v_mfma_f32_16x16x32_bf16 v[90:93], v[144:147], v[190:193], v[90:93]
	v_mfma_f32_16x16x32_bf16 v[82:85], v[136:139], v[198:201], v[82:85]
	v_mfma_f32_16x16x32_bf16 v[74:77], v[144:147], v[198:201], v[74:77]
	s_barrier
	s_add_i32 s5, 0, 0x1c000
	v_add_u32_e32 v156, s5, v237
	s_add_i32 s4, s4, s3
	ds_read_b128 v[202:205], v156
	ds_read_b128 v[206:209], v156 offset:1024
	ds_read_b128 v[210:213], v156 offset:2048
	ds_read_b128 v[214:217], v156 offset:3072
	v_lshl_add_u64 v[156:157], v[218:219], 0, s[84:85]
	s_mov_b32 m0, s4
	s_nop 0
	global_load_lds_dwordx4 v[156:157], off
	v_lshl_add_u64 v[156:157], v[224:225], 0, s[84:85]
	s_add_i32 m0, s4, 0x2000
	s_nop 0
	global_load_lds_dwordx4 v[156:157], off
	s_barrier
	s_waitcnt lgkmcnt(0)
	s_waitcnt lgkmcnt(0)
	v_mfma_f32_16x16x32_bf16 v[118:121], v[202:205], v[148:151], v[118:121]
	v_mfma_f32_16x16x32_bf16 v[114:117], v[210:213], v[148:151], v[114:117]
	v_mfma_f32_16x16x32_bf16 v[102:105], v[202:205], v[178:181], v[102:105]
	v_mfma_f32_16x16x32_bf16 v[94:97], v[210:213], v[178:181], v[94:97]
	v_mfma_f32_16x16x32_bf16 v[86:89], v[202:205], v[186:189], v[86:89]
	v_mfma_f32_16x16x32_bf16 v[78:81], v[210:213], v[186:189], v[78:81]
	v_mfma_f32_16x16x32_bf16 v[70:73], v[202:205], v[194:197], v[70:73]
	v_mfma_f32_16x16x32_bf16 v[66:69], v[210:213], v[194:197], v[66:69]
	v_mfma_f32_16x16x32_bf16 v[118:121], v[206:209], v[152:155], v[118:121]
	v_mfma_f32_16x16x32_bf16 v[114:117], v[214:217], v[152:155], v[114:117]
	v_mfma_f32_16x16x32_bf16 v[102:105], v[206:209], v[182:185], v[102:105]
	v_mfma_f32_16x16x32_bf16 v[94:97], v[214:217], v[182:185], v[94:97]
	v_mfma_f32_16x16x32_bf16 v[86:89], v[206:209], v[190:193], v[86:89]
	v_mfma_f32_16x16x32_bf16 v[78:81], v[214:217], v[190:193], v[78:81]
	v_mfma_f32_16x16x32_bf16 v[70:73], v[206:209], v[198:201], v[70:73]
	v_mfma_f32_16x16x32_bf16 v[66:69], v[214:217], v[198:201], v[66:69]
	s_mov_b32 m0, s12
	v_lshl_add_u64 v[156:157], v[230:231], 0, s[84:85]
	s_barrier
	ds_read_b128 v[148:151], v243 offset:49152
	ds_read_b128 v[152:155], v243 offset:50176
	ds_read_b128 v[178:181], v243 offset:51200
	ds_read_b128 v[182:185], v243 offset:52224
	ds_read_b128 v[186:189], v243 offset:53248
	ds_read_b128 v[190:193], v243 offset:54272
	ds_read_b128 v[194:197], v243 offset:55296
	ds_read_b128 v[198:201], v243 offset:56320
	global_load_lds_dwordx4 v[156:157], off
	v_lshl_add_u64 v[156:157], v[232:233], 0, s[84:85]
	s_mov_b32 m0, s28
	s_nop 0
	global_load_lds_dwordx4 v[156:157], off
	s_barrier
	s_waitcnt lgkmcnt(0)
	s_waitcnt lgkmcnt(0)
	v_mfma_f32_16x16x32_bf16 v[62:65], v[132:135], v[148:151], v[62:65]
	v_mfma_f32_16x16x32_bf16 v[58:61], v[140:143], v[148:151], v[58:61]
	v_mfma_f32_16x16x32_bf16 v[46:49], v[132:135], v[178:181], v[46:49]
	v_mfma_f32_16x16x32_bf16 v[42:45], v[140:143], v[178:181], v[42:45]
	v_mfma_f32_16x16x32_bf16 v[34:37], v[132:135], v[186:189], v[34:37]
	v_mfma_f32_16x16x32_bf16 v[26:29], v[140:143], v[186:189], v[26:29]
	v_mfma_f32_16x16x32_bf16 v[18:21], v[132:135], v[194:197], v[18:21]
	v_mfma_f32_16x16x32_bf16 v[10:13], v[140:143], v[194:197], v[10:13]
	v_mfma_f32_16x16x32_bf16 v[62:65], v[136:139], v[152:155], v[62:65]
	v_mfma_f32_16x16x32_bf16 v[58:61], v[144:147], v[152:155], v[58:61]
	v_mfma_f32_16x16x32_bf16 v[46:49], v[136:139], v[182:185], v[46:49]
	v_mfma_f32_16x16x32_bf16 v[42:45], v[144:147], v[182:185], v[42:45]
	v_mfma_f32_16x16x32_bf16 v[34:37], v[136:139], v[190:193], v[34:37]
	v_mfma_f32_16x16x32_bf16 v[26:29], v[144:147], v[190:193], v[26:29]
	v_mfma_f32_16x16x32_bf16 v[18:21], v[136:139], v[198:201], v[18:21]
	v_mfma_f32_16x16x32_bf16 v[10:13], v[144:147], v[198:201], v[10:13]
	s_barrier
	s_add_i32 s4, s5, s3
	v_lshl_add_u64 v[132:133], v[244:245], 0, s[84:85]
	s_mov_b32 m0, s4
	s_nop 0
	global_load_lds_dwordx4 v[132:133], off
	v_lshl_add_u64 v[132:133], v[246:247], 0, s[84:85]
	s_add_i32 m0, s4, 0x2000
	s_nop 0
	global_load_lds_dwordx4 v[132:133], off
	s_waitcnt vmcnt(6)
	s_barrier
	v_mfma_f32_16x16x32_bf16 v[54:57], v[202:205], v[148:151], v[54:57]
	v_mfma_f32_16x16x32_bf16 v[50:53], v[210:213], v[148:151], v[50:53]
	v_mfma_f32_16x16x32_bf16 v[38:41], v[202:205], v[178:181], v[38:41]
	v_mfma_f32_16x16x32_bf16 v[30:33], v[210:213], v[178:181], v[30:33]
	v_mfma_f32_16x16x32_bf16 v[22:25], v[202:205], v[186:189], v[22:25]
	v_mfma_f32_16x16x32_bf16 v[14:17], v[210:213], v[186:189], v[14:17]
	v_mfma_f32_16x16x32_bf16 v[6:9], v[202:205], v[194:197], v[6:9]
	v_mfma_f32_16x16x32_bf16 v[2:5], v[210:213], v[194:197], v[2:5]
	v_mfma_f32_16x16x32_bf16 v[54:57], v[206:209], v[152:155], v[54:57]
	v_mfma_f32_16x16x32_bf16 v[50:53], v[214:217], v[152:155], v[50:53]
	v_mfma_f32_16x16x32_bf16 v[38:41], v[206:209], v[182:185], v[38:41]
	v_mfma_f32_16x16x32_bf16 v[30:33], v[214:217], v[182:185], v[30:33]
	v_mfma_f32_16x16x32_bf16 v[22:25], v[206:209], v[190:193], v[22:25]
	v_mfma_f32_16x16x32_bf16 v[14:17], v[214:217], v[190:193], v[14:17]
	v_mfma_f32_16x16x32_bf16 v[6:9], v[206:209], v[198:201], v[6:9]
	v_mfma_f32_16x16x32_bf16 v[2:5], v[214:217], v[198:201], v[2:5]
	s_add_u32 s6, s6, 0x100
	s_addc_u32 s7, s7, 0
	v_lshl_add_u64 v[130:131], v[130:131], 0, s[86:87]
	s_cmp_ge_u32 s42, s13
	s_mov_b32 s4, s42
	s_barrier
	s_cbranch_scc0 .LBB0_649
	s_lshl_b32 s6, s23, 8
	v_lshl_or_b32 v178, s22, 8, v238
	v_add_u32_e32 v130, s6, v1
	v_ashrrev_i32_e32 v179, 31, v178
	v_lshlrev_b64 v[186:187], 1, v[178:179]
	v_ashrrev_i32_e32 v131, 31, v130
	v_lshl_add_u64 v[190:191], s[18:19], 0, v[186:187]
	v_lshlrev_b64 v[188:189], 11, v[130:131]
	v_lshl_add_u64 v[132:133], v[190:191], 0, v[188:189]
	global_load_dwordx4 v[192:195], v[132:133], off
	global_load_dwordx4 v[154:157], v[132:133], off offset:256
	v_or_b32_e32 v132, 16, v130
	v_ashrrev_i32_e32 v133, 31, v132
	v_lshlrev_b64 v[184:185], 11, v[132:133]
	v_lshl_add_u64 v[132:133], v[190:191], 0, v[184:185]
	global_load_dwordx4 v[150:153], v[132:133], off
	global_load_dwordx4 v[146:149], v[132:133], off offset:256
	v_or_b32_e32 v132, 32, v130
	v_ashrrev_i32_e32 v133, 31, v132
	v_lshlrev_b64 v[182:183], 11, v[132:133]
	v_or_b32_e32 v130, 48, v130
	v_lshl_add_u64 v[132:133], v[190:191], 0, v[182:183]
	v_ashrrev_i32_e32 v131, 31, v130
	global_load_dwordx4 v[142:145], v[132:133], off
	global_load_dwordx4 v[138:141], v[132:133], off offset:256
	v_lshlrev_b64 v[180:181], 11, v[130:131]
	v_lshl_add_u64 v[130:131], v[190:191], 0, v[180:181]
	global_load_dwordx4 v[134:137], v[130:131], off
	s_nop 0
	global_load_dwordx4 v[130:133], v[130:131], off offset:256
	v_mov_b32_e32 v169, v168
	s_mov_b64 s[4:5], 0x40000
	v_cmp_lt_i32_e32 vcc, v227, v222
	s_waitcnt vmcnt(0)
	v_lshlrev_b32_e32 v196, 16, v192
	v_and_b32_e32 v197, 0xffff0000, v192
	v_lshlrev_b32_e32 v192, 16, v193
	v_and_b32_e32 v193, 0xffff0000, v193
	v_lshlrev_b32_e32 v198, 16, v194
	v_and_b32_e32 v199, 0xffff0000, v194
	v_lshlrev_b32_e32 v194, 16, v195
	v_and_b32_e32 v195, 0xffff0000, v195
	v_pk_fma_f32 v[128:129], v[168:169], v[128:129], v[192:193]
	v_pk_fma_f32 v[126:127], v[170:171], v[126:127], v[196:197]
	v_pk_fma_f32 v[192:193], v[168:169], v[124:125], v[194:195]
	v_pk_fma_f32 v[124:125], v[170:171], v[122:123], v[198:199]
	v_mul_f32_e32 v122, v127, v127
	v_mul_f32_e32 v123, v129, v129
	v_fmac_f32_e32 v122, v126, v126
	v_fmac_f32_e32 v123, v128, v128
	v_add_f32_e32 v122, v122, v123
	v_mul_f32_e32 v123, v125, v125
	v_mul_f32_e32 v194, v193, v193
	v_fmac_f32_e32 v123, v124, v124
	v_fmac_f32_e32 v194, v192, v192
	v_add_f32_e32 v123, v123, v194
	v_add_f32_e32 v194, v122, v123
	v_cvt_pk_bf16_f32 v122, v126, v127
	v_cvt_pk_bf16_f32 v123, v128, v129
	v_lshlrev_b32_e32 v126, 16, v154
	v_and_b32_e32 v127, 0xffff0000, v154
	v_lshlrev_b32_e32 v128, 16, v155
	v_and_b32_e32 v129, 0xffff0000, v155
	v_lshlrev_b32_e32 v154, 16, v156
	v_and_b32_e32 v155, 0xffff0000, v156
	v_lshlrev_b32_e32 v156, 16, v157
	v_and_b32_e32 v157, 0xffff0000, v157
	v_pk_fma_f32 v[120:121], v[168:169], v[120:121], v[128:129]
	v_pk_fma_f32 v[118:119], v[170:171], v[118:119], v[126:127]
	v_pk_fma_f32 v[126:127], v[168:169], v[116:117], v[156:157]
	v_pk_fma_f32 v[116:117], v[170:171], v[114:115], v[154:155]
	v_mul_f32_e32 v114, v119, v119
	v_mul_f32_e32 v115, v121, v121
	v_fmac_f32_e32 v114, v118, v118
	v_fmac_f32_e32 v115, v120, v120
	v_add_f32_e32 v114, v114, v115
	v_mul_f32_e32 v115, v117, v117
	v_mul_f32_e32 v128, v127, v127
	v_fmac_f32_e32 v115, v116, v116
	v_fmac_f32_e32 v128, v126, v126
	v_add_f32_e32 v115, v115, v128
	v_add_f32_e32 v114, v114, v115
	v_cvt_pk_bf16_f32 v124, v124, v125
	v_cvt_pk_bf16_f32 v125, v192, v193
	v_add_f32_e32 v244, v194, v114
	v_cvt_pk_bf16_f32 v114, v118, v119
	v_cvt_pk_bf16_f32 v115, v120, v121
	v_lshlrev_b32_e32 v118, 16, v150
	v_and_b32_e32 v119, 0xffff0000, v150
	v_lshlrev_b32_e32 v120, 16, v151
	v_and_b32_e32 v121, 0xffff0000, v151
	v_pk_fma_f32 v[154:155], v[168:169], v[112:113], v[120:121]
	v_pk_fma_f32 v[156:157], v[170:171], v[110:111], v[118:119]
	v_lshlrev_b32_e32 v110, 16, v146
	v_and_b32_e32 v111, 0xffff0000, v146
	v_lshlrev_b32_e32 v112, 16, v147
	v_and_b32_e32 v113, 0xffff0000, v147
	v_lshlrev_b32_e32 v118, 16, v148
	v_and_b32_e32 v119, 0xffff0000, v148
	v_lshlrev_b32_e32 v120, 16, v149
	v_and_b32_e32 v121, 0xffff0000, v149
	v_pk_fma_f32 v[146:147], v[168:169], v[104:105], v[112:113]
	v_pk_fma_f32 v[192:193], v[170:171], v[102:103], v[110:111]
	v_pk_fma_f32 v[148:149], v[168:169], v[96:97], v[120:121]
	v_pk_fma_f32 v[198:199], v[170:171], v[94:95], v[118:119]
	v_lshlrev_b32_e32 v94, 16, v142
	v_and_b32_e32 v95, 0xffff0000, v142
	v_lshlrev_b32_e32 v96, 16, v143
	v_and_b32_e32 v97, 0xffff0000, v143
	v_lshlrev_b32_e32 v110, 16, v144
	v_and_b32_e32 v111, 0xffff0000, v144
	v_lshlrev_b32_e32 v112, 16, v145
	v_and_b32_e32 v113, 0xffff0000, v145
	v_pk_fma_f32 v[142:143], v[168:169], v[100:101], v[96:97]
	v_pk_fma_f32 v[194:195], v[170:171], v[98:99], v[94:95]
	v_pk_fma_f32 v[144:145], v[168:169], v[92:93], v[112:113]
	v_pk_fma_f32 v[196:197], v[170:171], v[90:91], v[110:111]
	v_lshlrev_b32_e32 v90, 16, v138
	v_and_b32_e32 v91, 0xffff0000, v138
	v_lshlrev_b32_e32 v92, 16, v139
	v_and_b32_e32 v93, 0xffff0000, v139
	v_lshlrev_b32_e32 v98, 16, v140
	v_and_b32_e32 v99, 0xffff0000, v140
	v_lshlrev_b32_e32 v100, 16, v141
	v_and_b32_e32 v101, 0xffff0000, v141
	v_pk_fma_f32 v[200:201], v[168:169], v[88:89], v[92:93]
	v_pk_fma_f32 v[208:209], v[170:171], v[86:87], v[90:91]
	v_pk_fma_f32 v[204:205], v[168:169], v[80:81], v[100:101]
	v_pk_fma_f32 v[210:211], v[170:171], v[78:79], v[98:99]
	v_lshlrev_b32_e32 v78, 16, v134
	v_and_b32_e32 v79, 0xffff0000, v134
	v_lshlrev_b32_e32 v80, 16, v135
	v_and_b32_e32 v81, 0xffff0000, v135
	v_lshlrev_b32_e32 v86, 16, v136
	v_and_b32_e32 v87, 0xffff0000, v136
	v_lshlrev_b32_e32 v88, 16, v137
	v_and_b32_e32 v89, 0xffff0000, v137
	v_cvt_pk_bf16_f32 v116, v116, v117
	v_cvt_pk_bf16_f32 v117, v126, v127
	v_lshlrev_b32_e32 v126, 16, v152
	v_and_b32_e32 v127, 0xffff0000, v152
	v_lshlrev_b32_e32 v128, 16, v153
	v_and_b32_e32 v129, 0xffff0000, v153
	v_pk_fma_f32 v[138:139], v[168:169], v[84:85], v[80:81]
	v_pk_fma_f32 v[202:203], v[170:171], v[82:83], v[78:79]
	v_pk_fma_f32 v[140:141], v[168:169], v[76:77], v[88:89]
	v_pk_fma_f32 v[206:207], v[170:171], v[74:75], v[86:87]
	v_lshlrev_b32_e32 v74, 16, v130
	v_and_b32_e32 v75, 0xffff0000, v130
	v_lshlrev_b32_e32 v76, 16, v131
	v_and_b32_e32 v77, 0xffff0000, v131
	v_lshlrev_b32_e32 v78, 16, v132
	v_and_b32_e32 v79, 0xffff0000, v132
	v_lshlrev_b32_e32 v80, 16, v133
	v_and_b32_e32 v81, 0xffff0000, v133
	v_lshl_add_u64 v[136:137], v[188:189], 0, s[4:5]
	s_mov_b64 s[4:5], 0x48000
	v_pk_fma_f32 v[150:151], v[168:169], v[108:109], v[128:129]
	v_pk_fma_f32 v[152:153], v[170:171], v[106:107], v[126:127]
	v_cvt_pk_bf16_f32 v106, v156, v157
	v_cvt_pk_bf16_f32 v107, v154, v155
	v_pk_fma_f32 v[212:213], v[168:169], v[72:73], v[76:77]
	v_cvt_pk_bf16_f32 v108, v152, v153
	v_cvt_pk_bf16_f32 v109, v150, v151
	v_cvt_pk_bf16_f32 v102, v192, v193
	v_cvt_pk_bf16_f32 v103, v146, v147
	v_cvt_pk_bf16_f32 v104, v198, v199
	v_cvt_pk_bf16_f32 v105, v148, v149
	v_cvt_pk_bf16_f32 v94, v194, v195
	v_cvt_pk_bf16_f32 v95, v142, v143
	v_cvt_pk_bf16_f32 v96, v196, v197
	v_cvt_pk_bf16_f32 v97, v144, v145
	v_cvt_pk_bf16_f32 v118, v208, v209
	v_cvt_pk_bf16_f32 v119, v200, v201
	v_cvt_pk_bf16_f32 v120, v210, v211
	v_cvt_pk_bf16_f32 v121, v204, v205
	v_cvt_pk_bf16_f32 v98, v202, v203
	v_cvt_pk_bf16_f32 v99, v138, v139
	v_cvt_pk_bf16_f32 v100, v206, v207
	v_cvt_pk_bf16_f32 v101, v140, v141
	v_pk_fma_f32 v[216:217], v[170:171], v[70:71], v[74:75]
	v_pk_fma_f32 v[214:215], v[168:169], v[68:69], v[80:81]
	v_pk_fma_f32 v[218:219], v[170:171], v[66:67], v[78:79]
	v_cvt_pk_bf16_f32 v126, v216, v217
	v_cvt_pk_bf16_f32 v127, v212, v213
	v_lshl_add_u64 v[66:67], v[190:191], 0, v[136:137]
	v_cvt_pk_bf16_f32 v128, v218, v219
	v_cvt_pk_bf16_f32 v129, v214, v215
	v_lshl_add_u64 v[134:135], v[188:189], 0, s[4:5]
	s_mov_b64 s[4:5], 0x50000
	global_load_dwordx4 v[110:113], v[66:67], off
	global_load_dwordx4 v[90:93], v[66:67], off offset:256
	v_lshl_add_u64 v[66:67], v[190:191], 0, v[134:135]
	v_lshl_add_u64 v[132:133], v[188:189], 0, s[4:5]
	s_mov_b64 s[4:5], 0x58000
	global_load_dwordx4 v[86:89], v[66:67], off
	global_load_dwordx4 v[82:85], v[66:67], off offset:256
	v_lshl_add_u64 v[66:67], v[190:191], 0, v[132:133]
	v_lshl_add_u64 v[130:131], v[188:189], 0, s[4:5]
	global_load_dwordx4 v[78:81], v[66:67], off
	global_load_dwordx4 v[74:77], v[66:67], off offset:256
	v_lshl_add_u64 v[66:67], v[190:191], 0, v[130:131]
	global_load_dwordx4 v[70:73], v[66:67], off
	s_nop 0
	global_load_dwordx4 v[66:69], v[66:67], off offset:256
	v_cndmask_b32_e32 v169, v221, v227, vcc
	v_lshl_add_u64 v[188:189], s[18:19], 0, v[188:189]
	v_lshlrev_b32_e32 v190, 2, v169
	v_lshl_add_u64 v[186:187], v[188:189], 0, v[186:187]
	global_store_dwordx4 v[186:187], v[122:125], off
	global_store_dwordx4 v[186:187], v[114:117], off offset:256
	s_nop 1
	v_mov_b32_e32 v114, v244
	s_nop 1
	v_permlane16_swap_b32_e32 v114, v244
	v_cmp_lt_i32_e32 vcc, v228, v222
	s_waitcnt lgkmcnt(0)
	v_add_f32_e32 v114, v244, v114
	v_cndmask_b32_e32 v169, v221, v228, vcc
	v_lshlrev_b32_e32 v191, 2, v169
	v_mov_b32_e32 v115, v114
	s_nop 1
	v_permlane32_swap_b32_e32 v115, v114
	s_and_saveexec_b64 s[4:5], s[38:39]
	s_cbranch_execz .LBB0_652
	s_waitcnt lgkmcnt(0)
	v_add_f32_e32 v114, v114, v115
	v_add_u32_e32 v115, s90, v239
	ds_write_b32 v115, v114
.LBB0_652:
	s_or_b64 exec, exec, s[4:5]
	v_mul_f32_e32 v114, v157, v157
	s_waitcnt lgkmcnt(0)
	v_mul_f32_e32 v115, v155, v155
	v_fmac_f32_e32 v114, v156, v156
	v_fmac_f32_e32 v115, v154, v154
	v_add_f32_e32 v114, v114, v115
	v_mul_f32_e32 v115, v153, v153
	v_mul_f32_e32 v116, v151, v151
	v_fmac_f32_e32 v115, v152, v152
	v_fmac_f32_e32 v116, v150, v150
	v_add_f32_e32 v115, v115, v116
	v_add_f32_e32 v114, v114, v115
	v_mul_f32_e32 v115, v193, v193
	v_mul_f32_e32 v116, v147, v147
	v_fmac_f32_e32 v115, v192, v192
	v_fmac_f32_e32 v116, v146, v146
	v_add_f32_e32 v115, v115, v116
	v_mul_f32_e32 v116, v199, v199
	v_mul_f32_e32 v117, v149, v149
	v_fmac_f32_e32 v116, v198, v198
	v_fmac_f32_e32 v117, v148, v148
	v_add_f32_e32 v116, v116, v117
	v_add_f32_e32 v115, v115, v116
	v_add_f32_e32 v114, v114, v115
	v_mov_b32_e32 v115, v114
	s_nop 1
	v_permlane16_swap_b32_e32 v115, v114
	v_lshl_add_u64 v[116:117], s[18:19], 0, v[184:185]
	v_lshl_add_u64 v[116:117], v[178:179], 1, v[116:117]
	global_store_dwordx4 v[116:117], v[106:109], off
	global_store_dwordx4 v[116:117], v[102:105], off offset:256
	s_waitcnt lgkmcnt(0)
	v_add_f32_e32 v114, v114, v115
	v_mov_b32_e32 v115, v114
	s_nop 1
	v_permlane32_swap_b32_e32 v115, v114
	s_and_saveexec_b64 s[4:5], s[38:39]
	s_cbranch_execz .LBB0_654
	s_waitcnt lgkmcnt(0)
	v_add_f32_e32 v102, v114, v115
	v_add_u32_e32 v103, s90, v239
	ds_write_b32 v103, v102 offset:256
.LBB0_654:
	s_or_b64 exec, exec, s[4:5]
	v_mul_f32_e32 v102, v195, v195
	v_mul_f32_e32 v103, v143, v143
	v_fmac_f32_e32 v102, v194, v194
	v_fmac_f32_e32 v103, v142, v142
	v_add_f32_e32 v102, v102, v103
	v_mul_f32_e32 v103, v197, v197
	v_mul_f32_e32 v104, v145, v145
	v_fmac_f32_e32 v103, v196, v196
	v_fmac_f32_e32 v104, v144, v144
	v_add_f32_e32 v103, v103, v104
	v_add_f32_e32 v102, v102, v103
	v_mul_f32_e32 v103, v209, v209
	v_mul_f32_e32 v104, v201, v201
	v_fmac_f32_e32 v103, v208, v208
	v_fmac_f32_e32 v104, v200, v200
	v_add_f32_e32 v103, v103, v104
	v_mul_f32_e32 v104, v211, v211
	v_mul_f32_e32 v105, v205, v205
	v_fmac_f32_e32 v104, v210, v210
	v_fmac_f32_e32 v105, v204, v204
	v_add_f32_e32 v104, v104, v105
	v_add_f32_e32 v103, v103, v104
	v_add_f32_e32 v102, v102, v103
	v_mov_b32_e32 v103, v102
	s_nop 1
	v_permlane16_swap_b32_e32 v103, v102
	v_lshl_add_u64 v[104:105], s[18:19], 0, v[182:183]
	v_lshl_add_u64 v[104:105], v[178:179], 1, v[104:105]
	global_store_dwordx4 v[104:105], v[94:97], off
	global_store_dwordx4 v[104:105], v[118:121], off offset:256
	s_waitcnt lgkmcnt(0)
	v_add_f32_e32 v102, v102, v103
	v_mov_b32_e32 v103, v102
	s_nop 1
	v_permlane32_swap_b32_e32 v103, v102
	s_and_saveexec_b64 s[4:5], s[38:39]
	s_cbranch_execz .LBB0_656
	s_waitcnt lgkmcnt(0)
	v_add_f32_e32 v94, v102, v103
	v_add_u32_e32 v95, s90, v239
	ds_write_b32 v95, v94 offset:512
.LBB0_656:
	s_or_b64 exec, exec, s[4:5]
	v_mul_f32_e32 v94, v203, v203
	v_mul_f32_e32 v95, v139, v139
	v_fmac_f32_e32 v94, v202, v202
	v_fmac_f32_e32 v95, v138, v138
	v_add_f32_e32 v94, v94, v95
	v_mul_f32_e32 v95, v207, v207
	v_mul_f32_e32 v96, v141, v141
	v_fmac_f32_e32 v95, v206, v206
	v_fmac_f32_e32 v96, v140, v140
	v_add_f32_e32 v95, v95, v96
	v_add_f32_e32 v94, v94, v95
	v_mul_f32_e32 v95, v217, v217
	v_mul_f32_e32 v96, v213, v213
	v_fmac_f32_e32 v95, v216, v216
	v_fmac_f32_e32 v96, v212, v212
	v_add_f32_e32 v95, v95, v96
	v_mul_f32_e32 v96, v219, v219
	v_mul_f32_e32 v97, v215, v215
	v_fmac_f32_e32 v96, v218, v218
	v_fmac_f32_e32 v97, v214, v214
	v_add_f32_e32 v96, v96, v97
	v_add_f32_e32 v95, v95, v96
	v_add_f32_e32 v94, v94, v95
	v_mov_b32_e32 v95, v94
	s_nop 1
	v_permlane16_swap_b32_e32 v95, v94
	v_lshl_add_u64 v[96:97], s[18:19], 0, v[180:181]
	v_lshl_add_u64 v[96:97], v[178:179], 1, v[96:97]
	global_store_dwordx4 v[96:97], v[98:101], off
	global_store_dwordx4 v[96:97], v[126:129], off offset:256
	s_waitcnt lgkmcnt(0)
	v_add_f32_e32 v94, v94, v95
	v_mov_b32_e32 v95, v94
	s_nop 1
	v_permlane32_swap_b32_e32 v95, v94
	s_and_saveexec_b64 s[4:5], s[38:39]
	s_cbranch_execz .LBB0_658
	s_waitcnt lgkmcnt(0)
	v_add_f32_e32 v94, v94, v95
	v_add_u32_e32 v95, s90, v239
	ds_write_b32 v95, v94 offset:768
.LBB0_658:
	s_or_b64 exec, exec, s[4:5]
	s_waitcnt vmcnt(15)
	v_lshlrev_b32_e32 v94, 16, v110
	s_waitcnt lgkmcnt(0)
	v_and_b32_e32 v95, 0xffff0000, v110
	v_lshlrev_b32_e32 v96, 16, v111
	v_and_b32_e32 v97, 0xffff0000, v111
	v_mov_b32_e32 v169, v168
	v_lshlrev_b32_e32 v98, 16, v112
	v_and_b32_e32 v99, 0xffff0000, v112
	v_lshlrev_b32_e32 v100, 16, v113
	v_and_b32_e32 v101, 0xffff0000, v113
	v_pk_fma_f32 v[64:65], v[168:169], v[64:65], v[96:97]
	v_pk_fma_f32 v[62:63], v[170:171], v[62:63], v[94:95]
	v_pk_fma_f32 v[94:95], v[168:169], v[60:61], v[100:101]
	v_pk_fma_f32 v[60:61], v[170:171], v[58:59], v[98:99]
	v_mul_f32_e32 v58, v63, v63
	v_mul_f32_e32 v59, v65, v65
	v_fmac_f32_e32 v58, v62, v62
	v_fmac_f32_e32 v59, v64, v64
	v_add_f32_e32 v58, v58, v59
	v_mul_f32_e32 v59, v61, v61
	v_mul_f32_e32 v96, v95, v95
	v_fmac_f32_e32 v59, v60, v60
	v_fmac_f32_e32 v96, v94, v94
	v_add_f32_e32 v59, v59, v96
	v_add_f32_e32 v96, v58, v59
	v_cvt_pk_bf16_f32 v58, v62, v63
	v_cvt_pk_bf16_f32 v59, v64, v65
	s_waitcnt vmcnt(14)
	v_lshlrev_b32_e32 v62, 16, v90
	v_and_b32_e32 v63, 0xffff0000, v90
	v_lshlrev_b32_e32 v64, 16, v91
	v_and_b32_e32 v65, 0xffff0000, v91
	v_pk_fma_f32 v[56:57], v[168:169], v[56:57], v[64:65]
	v_pk_fma_f32 v[54:55], v[170:171], v[54:55], v[62:63]
	v_lshlrev_b32_e32 v90, 16, v92
	v_and_b32_e32 v91, 0xffff0000, v92
	v_lshlrev_b32_e32 v92, 16, v93
	v_and_b32_e32 v93, 0xffff0000, v93
	v_mul_f32_e32 v62, v55, v55
	v_mul_f32_e32 v63, v57, v57
	v_pk_fma_f32 v[52:53], v[168:169], v[52:53], v[92:93]
	v_pk_fma_f32 v[50:51], v[170:171], v[50:51], v[90:91]
	v_fmac_f32_e32 v62, v54, v54
	v_fmac_f32_e32 v63, v56, v56
	v_add_f32_e32 v62, v62, v63
	v_mul_f32_e32 v63, v51, v51
	v_mul_f32_e32 v64, v53, v53
	v_fmac_f32_e32 v63, v50, v50
	v_fmac_f32_e32 v64, v52, v52
	v_cvt_pk_bf16_f32 v60, v60, v61
	v_cvt_pk_bf16_f32 v61, v94, v95
	v_add_f32_e32 v63, v63, v64
	v_cvt_pk_bf16_f32 v90, v54, v55
	v_cvt_pk_bf16_f32 v91, v56, v57
	v_cvt_pk_bf16_f32 v92, v50, v51
	v_cvt_pk_bf16_f32 v93, v52, v53
	s_waitcnt vmcnt(13)
	v_lshlrev_b32_e32 v50, 16, v86
	v_and_b32_e32 v51, 0xffff0000, v86
	v_lshlrev_b32_e32 v52, 16, v87
	v_and_b32_e32 v53, 0xffff0000, v87
	v_lshlrev_b32_e32 v54, 16, v88
	v_and_b32_e32 v55, 0xffff0000, v88
	v_lshlrev_b32_e32 v56, 16, v89
	v_and_b32_e32 v57, 0xffff0000, v89
	v_add_f32_e32 v62, v62, v63
	v_pk_fma_f32 v[48:49], v[168:169], v[48:49], v[52:53]
	v_pk_fma_f32 v[50:51], v[170:171], v[46:47], v[50:51]
	v_pk_fma_f32 v[46:47], v[168:169], v[44:45], v[56:57]
	v_pk_fma_f32 v[52:53], v[170:171], v[42:43], v[54:55]
	s_waitcnt vmcnt(12)
	v_lshlrev_b32_e32 v54, 16, v82
	v_and_b32_e32 v55, 0xffff0000, v82
	v_lshlrev_b32_e32 v56, 16, v83
	v_and_b32_e32 v57, 0xffff0000, v83
	v_add_f32_e32 v94, v96, v62
	v_pk_fma_f32 v[40:41], v[168:169], v[40:41], v[56:57]
	v_pk_fma_f32 v[62:63], v[170:171], v[38:39], v[54:55]
	s_waitcnt vmcnt(11)
	v_lshlrev_b32_e32 v38, 16, v78
	v_and_b32_e32 v39, 0xffff0000, v78
	v_lshlrev_b32_e32 v56, 16, v79
	v_and_b32_e32 v57, 0xffff0000, v79
	v_lshlrev_b32_e32 v78, 16, v80
	v_and_b32_e32 v79, 0xffff0000, v80
	v_lshlrev_b32_e32 v80, 16, v81
	v_and_b32_e32 v81, 0xffff0000, v81
	v_lshlrev_b32_e32 v82, 16, v85
	v_and_b32_e32 v83, 0xffff0000, v85
	v_pk_fma_f32 v[36:37], v[168:169], v[36:37], v[56:57]
	v_pk_fma_f32 v[38:39], v[170:171], v[34:35], v[38:39]
	v_pk_fma_f32 v[34:35], v[168:169], v[28:29], v[80:81]
	v_pk_fma_f32 v[56:57], v[170:171], v[26:27], v[78:79]
	s_waitcnt vmcnt(10)
	v_lshlrev_b32_e32 v78, 16, v74
	v_and_b32_e32 v79, 0xffff0000, v74
	v_lshlrev_b32_e32 v80, 16, v76
	v_and_b32_e32 v81, 0xffff0000, v76
	v_pk_fma_f32 v[54:55], v[168:169], v[32:33], v[82:83]
	v_lshlrev_b32_e32 v82, 16, v77
	v_and_b32_e32 v83, 0xffff0000, v77
	v_pk_fma_f32 v[76:77], v[170:171], v[22:23], v[78:79]
	v_pk_fma_f32 v[78:79], v[170:171], v[14:15], v[80:81]
	s_waitcnt vmcnt(9)
	v_lshlrev_b32_e32 v22, 16, v70
	v_and_b32_e32 v23, 0xffff0000, v70
	v_lshlrev_b32_e32 v80, 16, v72
	v_and_b32_e32 v81, 0xffff0000, v72
	v_lshlrev_b32_e32 v72, 16, v73
	v_and_b32_e32 v73, 0xffff0000, v73
	v_pk_fma_f32 v[22:23], v[170:171], v[18:19], v[22:23]
	v_pk_fma_f32 v[18:19], v[168:169], v[12:13], v[72:73]
	s_waitcnt vmcnt(8)
	v_lshlrev_b32_e32 v72, 16, v66
	v_and_b32_e32 v73, 0xffff0000, v66
	v_lshlrev_b32_e32 v66, 16, v67
	v_and_b32_e32 v67, 0xffff0000, v67
	v_pk_fma_f32 v[8:9], v[168:169], v[8:9], v[66:67]
	v_pk_fma_f32 v[66:67], v[170:171], v[6:7], v[72:73]
	v_mov_b32_e32 v72, v94
	s_nop 1
	v_permlane16_swap_b32_e32 v72, v94
	v_lshlrev_b32_e32 v70, 16, v71
	v_and_b32_e32 v71, 0xffff0000, v71
	v_pk_fma_f32 v[20:21], v[168:169], v[20:21], v[70:71]
	v_pk_fma_f32 v[70:71], v[170:171], v[10:11], v[80:81]
	s_waitcnt lgkmcnt(0)
	v_add_f32_e32 v72, v94, v72
	ds_bpermute_b32 v73, v191, v72
	v_lshlrev_b32_e32 v80, 16, v68
	v_and_b32_e32 v81, 0xffff0000, v68
	v_lshlrev_b32_e32 v68, 16, v69
	v_and_b32_e32 v69, 0xffff0000, v69
	v_lshlrev_b32_e32 v64, 16, v84
	v_and_b32_e32 v65, 0xffff0000, v84
	v_lshlrev_b32_e32 v74, 16, v75
	v_and_b32_e32 v75, 0xffff0000, v75
	v_pk_fma_f32 v[6:7], v[168:169], v[4:5], v[68:69]
	v_pk_fma_f32 v[68:69], v[170:171], v[2:3], v[80:81]
	v_lshl_add_u64 v[80:81], s[18:19], 0, v[136:137]
	v_pk_fma_f32 v[64:65], v[170:171], v[30:31], v[64:65]
	v_pk_fma_f32 v[24:25], v[168:169], v[24:25], v[74:75]
	v_pk_fma_f32 v[74:75], v[168:169], v[16:17], v[82:83]
	v_lshl_add_u64 v[80:81], v[178:179], 1, v[80:81]
	v_cvt_pk_bf16_f32 v42, v50, v51
	v_cvt_pk_bf16_f32 v43, v48, v49
	v_cvt_pk_bf16_f32 v44, v52, v53
	v_cvt_pk_bf16_f32 v45, v46, v47
	v_cvt_pk_bf16_f32 v30, v62, v63
	v_cvt_pk_bf16_f32 v31, v40, v41
	v_cvt_pk_bf16_f32 v32, v64, v65
	v_cvt_pk_bf16_f32 v33, v54, v55
	v_cvt_pk_bf16_f32 v26, v38, v39
	v_cvt_pk_bf16_f32 v27, v36, v37
	v_cvt_pk_bf16_f32 v28, v56, v57
	v_cvt_pk_bf16_f32 v29, v34, v35
	v_cvt_pk_bf16_f32 v14, v76, v77
	v_cvt_pk_bf16_f32 v15, v24, v25
	v_cvt_pk_bf16_f32 v16, v78, v79
	v_cvt_pk_bf16_f32 v17, v74, v75
	v_cvt_pk_bf16_f32 v10, v22, v23
	v_cvt_pk_bf16_f32 v11, v20, v21
	v_cvt_pk_bf16_f32 v12, v70, v71
	v_cvt_pk_bf16_f32 v13, v18, v19
	v_cvt_pk_bf16_f32 v2, v66, v67
	v_cvt_pk_bf16_f32 v3, v8, v9
	v_cvt_pk_bf16_f32 v4, v68, v69
	v_cvt_pk_bf16_f32 v5, v6, v7
	global_store_dwordx4 v[80:81], v[58:61], off
	global_store_dwordx4 v[80:81], v[90:93], off offset:256
	s_and_saveexec_b64 s[4:5], s[38:39]
	s_cbranch_execz .LBB0_660
	s_waitcnt lgkmcnt(0)
	v_add_f32_e32 v58, v72, v73
	v_add_u32_e32 v59, s90, v240
	ds_write_b32 v59, v58
.LBB0_660:
	s_or_b64 exec, exec, s[4:5]
	v_mul_f32_e32 v51, v51, v51
	v_mul_f32_e32 v49, v49, v49
	v_fmac_f32_e32 v51, v50, v50
	v_fmac_f32_e32 v49, v48, v48
	v_add_f32_e32 v48, v51, v49
	v_mul_f32_e32 v49, v53, v53
	v_mul_f32_e32 v47, v47, v47
	v_fmac_f32_e32 v49, v52, v52
	v_fmac_f32_e32 v47, v46, v46
	v_add_f32_e32 v46, v49, v47
	v_mul_f32_e32 v47, v63, v63
	v_mul_f32_e32 v41, v41, v41
	v_fmac_f32_e32 v47, v62, v62
	v_fmac_f32_e32 v41, v40, v40
	v_add_f32_e32 v40, v47, v41
	v_mul_f32_e32 v41, v65, v65
	v_mul_f32_e32 v47, v55, v55
	v_fmac_f32_e32 v41, v64, v64
	v_fmac_f32_e32 v47, v54, v54
	v_add_f32_e32 v41, v41, v47
	v_add_f32_e32 v46, v48, v46
	v_add_f32_e32 v40, v40, v41
	v_add_f32_e32 v40, v46, v40
	v_mov_b32_e32 v41, v40
	s_nop 1
	v_permlane16_swap_b32_e32 v41, v40
	v_lshl_add_u64 v[46:47], s[18:19], 0, v[134:135]
	v_lshl_add_u64 v[46:47], v[178:179], 1, v[46:47]
	global_store_dwordx4 v[46:47], v[42:45], off
	global_store_dwordx4 v[46:47], v[30:33], off offset:256
	s_waitcnt lgkmcnt(0)
	v_add_f32_e32 v40, v40, v41
	v_mov_b32_e32 v41, v40
	s_nop 1
	v_permlane32_swap_b32_e32 v41, v40
	s_and_saveexec_b64 s[4:5], s[38:39]
	s_cbranch_execz .LBB0_662
	s_waitcnt lgkmcnt(0)
	v_add_f32_e32 v30, v40, v41
	v_add_u32_e32 v31, s90, v240
	ds_write_b32 v31, v30 offset:256
.LBB0_662:
	s_or_b64 exec, exec, s[4:5]
	v_mul_f32_e32 v30, v39, v39
	v_mul_f32_e32 v31, v37, v37
	v_fmac_f32_e32 v30, v38, v38
	v_fmac_f32_e32 v31, v36, v36
	v_add_f32_e32 v30, v30, v31
	v_mul_f32_e32 v31, v57, v57
	v_mul_f32_e32 v32, v35, v35
	v_fmac_f32_e32 v31, v56, v56
	v_fmac_f32_e32 v32, v34, v34
	v_add_f32_e32 v31, v31, v32
	v_add_f32_e32 v30, v30, v31
	v_mul_f32_e32 v31, v77, v77
	v_mul_f32_e32 v25, v25, v25
	v_fmac_f32_e32 v31, v76, v76
	v_fmac_f32_e32 v25, v24, v24
	v_add_f32_e32 v24, v31, v25
	v_mul_f32_e32 v25, v79, v79
	v_mul_f32_e32 v31, v75, v75
	v_fmac_f32_e32 v25, v78, v78
	v_fmac_f32_e32 v31, v74, v74
	v_add_f32_e32 v25, v25, v31
	v_add_f32_e32 v24, v24, v25
	v_add_f32_e32 v24, v30, v24
	v_mov_b32_e32 v25, v24
	s_nop 1
	v_permlane16_swap_b32_e32 v25, v24
	v_lshl_add_u64 v[30:31], s[18:19], 0, v[132:133]
	v_lshl_add_u64 v[30:31], v[178:179], 1, v[30:31]
	global_store_dwordx4 v[30:31], v[26:29], off
	global_store_dwordx4 v[30:31], v[14:17], off offset:256
	s_waitcnt lgkmcnt(0)
	v_add_f32_e32 v24, v24, v25
	v_mov_b32_e32 v25, v24
	s_nop 1
	v_permlane32_swap_b32_e32 v25, v24
	s_and_saveexec_b64 s[4:5], s[38:39]
	s_cbranch_execz .LBB0_664
	s_waitcnt lgkmcnt(0)
	v_add_f32_e32 v14, v24, v25
	v_add_u32_e32 v15, s90, v240
	ds_write_b32 v15, v14 offset:512
.LBB0_664:
	s_or_b64 exec, exec, s[4:5]
	v_mul_f32_e32 v14, v23, v23
	v_mul_f32_e32 v15, v21, v21
	v_fmac_f32_e32 v14, v22, v22
	v_fmac_f32_e32 v15, v20, v20
	v_add_f32_e32 v14, v14, v15
	v_mul_f32_e32 v15, v71, v71
	v_mul_f32_e32 v16, v19, v19
	v_fmac_f32_e32 v15, v70, v70
	v_fmac_f32_e32 v16, v18, v18
	v_add_f32_e32 v15, v15, v16
	v_add_f32_e32 v14, v14, v15
	v_mul_f32_e32 v15, v67, v67
	v_mul_f32_e32 v9, v9, v9
	v_fmac_f32_e32 v15, v66, v66
	v_fmac_f32_e32 v9, v8, v8
	v_add_f32_e32 v8, v15, v9
	v_mul_f32_e32 v9, v69, v69
	v_mul_f32_e32 v7, v7, v7
	v_fmac_f32_e32 v9, v68, v68
	v_fmac_f32_e32 v7, v6, v6
	v_add_f32_e32 v6, v9, v7
	v_add_f32_e32 v6, v8, v6
	v_add_f32_e32 v6, v14, v6
	v_mov_b32_e32 v7, v6
	s_nop 1
	v_permlane16_swap_b32_e32 v7, v6
	v_lshl_add_u64 v[8:9], s[18:19], 0, v[130:131]
	v_lshl_add_u64 v[8:9], v[178:179], 1, v[8:9]
	global_store_dwordx4 v[8:9], v[10:13], off
	global_store_dwordx4 v[8:9], v[2:5], off offset:256
	s_waitcnt lgkmcnt(0)
	v_add_f32_e32 v6, v6, v7
	v_mov_b32_e32 v7, v6
	s_nop 1
	v_permlane32_swap_b32_e32 v7, v6
	s_and_saveexec_b64 s[4:5], s[38:39]
	s_cbranch_execz .LBB0_666
	s_waitcnt lgkmcnt(0)
	v_add_f32_e32 v2, v6, v7
	v_add_u32_e32 v3, s90, v240
	ds_write_b32 v3, v2 offset:768
